# L1 in-projection epilogue: eight row-scale loads issued at the block top so the per-group wait no longer drains the previous group's stores
# speedup vs baseline: 1.0043x; 1.0012x over previous
; DI unsigned pk2(float lo, float hi) { f32x2 v = {lo, hi}; bf16x2_t b = __builtin_convertvector(v, bf16x2_t); return __builtin_bit_cast(unsigned, b); }
; DI float rs_from_ss(u64 ssq) { return rsqrtf((float)ssq * (1.f / (1048576.f * 1024.f)) + EPS); }
;     DI void operator()(const AccT& acc, const Unit& u, int wr, int wc, int fr, int fq) const {
;         const int row0 = u.pm * 256 + wr * 64 + fr, col0 = u.pn * 256 + wc * 32 + 8 * fq;
; #pragma unroll
;         for (int ai = 0; ai < 2; ++ai)
; #pragma unroll
;             for (int m = 0; m < 4; ++m) { const int row = row0 + ai * 128 + m * 16;
;                 const float s = rs_from_ss(((const u64*)sc)[row]);
;                 bf16_t* rowp = O + (size_t)row * 2048 + col0;
; #pragma unroll
;                 for (int bj = 0; bj < 2; ++bj) { const f32x4 v0 = acc[ai][bj][m][0] * s, v1 = acc[ai][bj][m][1] * s;
;                     u32x4 w; w.x = pk2(v0[0], v0[1]); w.y = pk2(v0[2], v0[3]); w.z = pk2(v1[0], v1[1]); w.w = pk2(v1[2], v1[3]);
;                     *(u32x4*)(rowp + bj * 128) = w;
;                     if (u.pn >= 6) { bf16_t* kt = KT + (size_t)(col0 + bj * 128 - 1536) * S + row;
;                         kt[0] = (bf16_t)(w.x & 0xffffu); kt[(size_t)S] = (bf16_t)(w.x >> 16); kt[(size_t)2 * S] = (bf16_t)(w.y & 0xffffu); kt[(size_t)3 * S] = (bf16_t)(w.y >> 16);
;                         kt[(size_t)4 * S] = (bf16_t)(w.z & 0xffffu); kt[(size_t)5 * S] = (bf16_t)(w.z >> 16); kt[(size_t)6 * S] = (bf16_t)(w.w & 0xffffu); kt[(size_t)7 * S] = (bf16_t)(w.w >> 16); } } }
.LBB0_1306:
	v_lshl_add_u32 v144, s10, 8, v156
	v_ashrrev_i32_e32 v145, 31, v144
	v_lshl_add_u64 v[150:151], v[144:145], 3, s[4:5]
	global_load_dwordx2 v[200:201], v[150:151], off
	global_load_dwordx2 v[202:203], v[150:151], off offset:128
	global_load_dwordx2 v[204:205], v[150:151], off offset:256
	global_load_dwordx2 v[206:207], v[150:151], off offset:384
	global_load_dwordx2 v[208:209], v[150:151], off offset:1024
	global_load_dwordx2 v[210:211], v[150:151], off offset:1152
	global_load_dwordx2 v[212:213], v[150:151], off offset:1280
	global_load_dwordx2 v[214:215], v[150:151], off offset:1408
	s_nop 1
	v_lshl_or_b32 v152, s8, 8, v158
	s_cmp_gt_i32 s8, 5
	v_ashrrev_i32_e32 v153, 31, v152
	s_cselect_b64 s[10:11], -1, 0
	s_cmp_lt_i32 s8, 6
	s_waitcnt vmcnt(7)
	v_ffbh_u32_e32 v148, v201
	v_min_u32_e32 v149, 32, v148
	v_lshlrev_b64 v[146:147], v149, v[200:201]
	v_min_u32_e32 v146, 1, v146
	v_or_b32_e32 v146, v147, v146
	v_cvt_f32_u32_e32 v146, v146
	v_sub_u32_e32 v147, 32, v149
	v_add_u32_e32 v148, 0xfffffa00, v152
	v_ldexp_f32 v146, v146, v147
	v_fmamk_f32 v146, v146, 0x30800000, v162
	v_mul_f32_e32 v147, 0x4b800000, v146
	v_cmp_gt_f32_e32 vcc, s63, v146
	s_nop 1
	v_cndmask_b32_e32 v146, v146, v147, vcc
	v_rsq_f32_e32 v149, v146
	v_lshlrev_b64 v[146:147], 12, v[144:145]
	v_lshl_add_u64 v[146:147], s[2:3], 0, v[146:147]
	v_lshl_add_u64 v[146:147], v[152:153], 1, v[146:147]
	v_mul_f32_e32 v154, 0x45800000, v149
	v_cndmask_b32_e32 v154, v149, v154, vcc
	v_pk_mul_f32 v[126:127], v[126:127], v[154:155] op_sel_hi:[1,0]
	v_pk_mul_f32 v[124:125], v[124:125], v[154:155] op_sel_hi:[1,0]
	v_pk_mul_f32 v[164:165], v[122:123], v[154:155] op_sel_hi:[1,0]
	v_pk_mul_f32 v[122:123], v[120:121], v[154:155] op_sel_hi:[1,0]
	v_cvt_pk_bf16_f32 v120, v124, v125
	v_cvt_pk_bf16_f32 v121, v126, v127
	v_cvt_pk_bf16_f32 v122, v122, v123
	v_cvt_pk_bf16_f32 v123, v164, v165
	v_ashrrev_i32_e32 v149, 31, v148
	global_store_dwordx4 v[146:147], v[120:123], off
	s_cbranch_scc1 .LBB0_1308
	v_lshlrev_b64 v[124:125], 15, v[148:149]
	v_lshl_add_u64 v[124:125], s[12:13], 0, v[124:125]
	v_lshl_add_u64 v[124:125], v[144:145], 1, v[124:125]
	v_add_co_u32_e32 v126, vcc, 0x8000, v124
	global_store_short v[124:125], v120, off
	s_nop 0
	v_addc_co_u32_e32 v127, vcc, 0, v125, vcc
	global_store_short_d16_hi v[126:127], v120, off
	v_add_co_u32_e32 v126, vcc, 0x10000, v124
	s_nop 1
	v_addc_co_u32_e32 v127, vcc, 0, v125, vcc
	global_store_short v[126:127], v121, off
	v_add_co_u32_e32 v126, vcc, 0x18000, v124
	s_nop 1
	v_addc_co_u32_e32 v127, vcc, 0, v125, vcc
	v_add_co_u32_e32 v120, vcc, 0x20000, v124
	global_store_short_d16_hi v[126:127], v121, off
	s_nop 0
	v_addc_co_u32_e32 v121, vcc, 0, v125, vcc
	global_store_short v[120:121], v122, off
	v_add_co_u32_e32 v120, vcc, 0x28000, v124
	s_nop 1
	v_addc_co_u32_e32 v121, vcc, 0, v125, vcc
	global_store_short_d16_hi v[120:121], v122, off
	v_add_co_u32_e32 v120, vcc, 0x30000, v124
	s_nop 1
	v_addc_co_u32_e32 v121, vcc, 0, v125, vcc
	global_store_short v[120:121], v123, off
	v_add_co_u32_e32 v120, vcc, 0x38000, v124
	s_nop 1
	v_addc_co_u32_e32 v121, vcc, 0, v125, vcc
	global_store_short_d16_hi v[120:121], v123, off
